# attention band mask: one compare + one select per score (was ~11 instructions each, four copies per key tile)
# baseline (speedup 1.0000x reference)
.LBB0_979:
	ds_read_b128 v[120:123], v3
	ds_read_b128 v[124:127], v3 offset:64
	ds_read_b128 v[128:131], v3 offset:2304
	ds_read_b128 v[116:119], v3 offset:2368
	ds_read2_b64 v[100:103], v180 offset1:4
	s_waitcnt lgkmcnt(4)
	v_mfma_f32_16x16x32_bf16 v[104:107], v[120:123], v[84:87], 0
	v_add_u32_e32 v108, 0x1000, v180
	v_add_u32_e32 v109, 0x2000, v180
	v_add_u32_e32 v136, 0x3000, v180
	s_waitcnt lgkmcnt(3)
	v_mfma_f32_16x16x32_bf16 v[132:135], v[124:127], v[80:83], v[104:107]
	ds_read2_b64 v[112:115], v108 offset0:32 offset1:36
	ds_read2_b64 v[108:111], v109 offset0:64 offset1:68
	s_nop 0
	ds_read2_b64 v[104:107], v136 offset0:96 offset1:100
	v_cndmask_b32_e64 v148, 0, 1, s[60:61]
	v_add_u32_e32 v182, s25, v166
	s_waitcnt lgkmcnt(5)
	v_mfma_f32_16x16x32_bf16 v[136:139], v[128:131], v[84:87], 0
	v_cmp_ne_u32_e64 s[44:45], 1, v148
	s_andn2_b64 vcc, exec, s[60:61]
	s_waitcnt lgkmcnt(4)
	v_mfma_f32_16x16x32_bf16 v[136:139], v[116:119], v[80:83], v[136:139]
	s_cbranch_vccnz .LBB0_981
	v_sub_u32_e32 v204, v182, v142
	v_add_u32_e32 v205, 16, v204
	s_and_b64 vcc, exec, s[42:43]
	s_cbranch_vccz .Lam_le_0
	v_cmp_le_i32_e32 vcc, 0, v204
	v_cmp_ge_i32_e64 s[96:97], v204, -1
	v_cmp_ge_i32_e64 s[98:99], v204, -2
	v_cndmask_b32_e32 v132, v241, v132, vcc
	v_cmp_le_i32_e32 vcc, -3, v204
	v_cndmask_b32_e64 v133, v241, v133, s[96:97]
	v_cmp_ge_i32_e64 s[96:97], v205, 0
	v_cndmask_b32_e64 v134, v241, v134, s[98:99]
	v_cmp_ge_i32_e64 s[98:99], v205, -1
	v_cndmask_b32_e32 v135, v241, v135, vcc
	v_cmp_le_i32_e32 vcc, -2, v205
	v_cndmask_b32_e64 v136, v241, v136, s[96:97]
	v_cmp_ge_i32_e64 s[96:97], v205, -3
	v_cndmask_b32_e64 v137, v241, v137, s[98:99]
	v_cndmask_b32_e32 v138, v241, v138, vcc
	v_cndmask_b32_e64 v139, v241, v139, s[96:97]
	s_branch .Lam_done_0
.Lam_le_0:
	v_cmp_ge_i32_e32 vcc, 0, v204
	v_cmp_le_i32_e64 s[96:97], v204, -1
	v_cmp_le_i32_e64 s[98:99], v204, -2
	v_cndmask_b32_e32 v132, v241, v132, vcc
	v_cmp_ge_i32_e32 vcc, -3, v204
	v_cndmask_b32_e64 v133, v241, v133, s[96:97]
	v_cmp_le_i32_e64 s[96:97], v205, 0
	v_cndmask_b32_e64 v134, v241, v134, s[98:99]
	v_cmp_le_i32_e64 s[98:99], v205, -1
	v_cndmask_b32_e32 v135, v241, v135, vcc
	v_cmp_ge_i32_e32 vcc, -2, v205
	v_cndmask_b32_e64 v136, v241, v136, s[96:97]
	v_cmp_le_i32_e64 s[96:97], v205, -3
	v_cndmask_b32_e64 v137, v241, v137, s[98:99]
	v_cndmask_b32_e32 v138, v241, v138, vcc
	v_cndmask_b32_e64 v139, v241, v139, s[96:97]
.Lam_done_0:
.LBB0_981:
	v_max_f32_e32 v148, v133, v133
	v_max_f32_e32 v149, v132, v132
	v_max_f32_e32 v148, v149, v148
	v_max_f32_e32 v149, v135, v135
	v_max_f32_e32 v152, v134, v134
	v_max_f32_e32 v149, v152, v149
	s_nop 0
	v_max_f32_e32 v152, v139, v139
	v_max_f32_e32 v153, v138, v138
	v_max_f32_e32 v152, v153, v152
	v_max3_f32 v152, v136, v137, v152
	v_max3_f32 v148, v148, v149, v152
	ds_bpermute_b32 v149, v0, v148
	s_waitcnt lgkmcnt(0)
	v_max_f32_e32 v149, v149, v149
	v_max_f32_e32 v148, v148, v149
	ds_bpermute_b32 v149, v2, v148
	s_waitcnt lgkmcnt(0)
	v_max3_f32 v181, v179, v148, v149
	v_cmp_neq_f32_e32 vcc, v181, v179
	s_cbranch_vccz .LBB0_983
	v_sub_f32_e32 v148, v179, v181
	v_exp_f32_e32 v184, v148
	s_nop 0
	v_mul_f32_e32 v147, v147, v184
	v_pk_mul_f32 v[98:99], v[98:99], v[184:185] op_sel_hi:[1,0]
	v_pk_mul_f32 v[96:97], v[96:97], v[184:185] op_sel_hi:[1,0]
	v_pk_mul_f32 v[94:95], v[94:95], v[184:185] op_sel_hi:[1,0]
	v_pk_mul_f32 v[92:93], v[92:93], v[184:185] op_sel_hi:[1,0]
	v_pk_mul_f32 v[78:79], v[78:79], v[184:185] op_sel_hi:[1,0]
	v_pk_mul_f32 v[76:77], v[76:77], v[184:185] op_sel_hi:[1,0]
	v_pk_mul_f32 v[66:67], v[66:67], v[184:185] op_sel_hi:[1,0]
	v_pk_mul_f32 v[64:65], v[64:65], v[184:185] op_sel_hi:[1,0]
.LBB0_983:
	v_sub_f32_e32 v132, v132, v181
	v_exp_f32_e32 v183, v132
	v_sub_f32_e32 v132, v136, v181
	v_exp_f32_e32 v179, v132
	v_sub_f32_e32 v132, v133, v181
	v_exp_f32_e32 v185, v132
	v_sub_f32_e32 v132, v137, v181
	v_exp_f32_e32 v184, v132
	v_sub_f32_e32 v132, v134, v181
	v_exp_f32_e32 v187, v132
	v_sub_f32_e32 v132, v138, v181
	v_exp_f32_e32 v186, v132
	v_sub_f32_e32 v132, v135, v181
	v_exp_f32_e32 v189, v132
	v_sub_f32_e32 v132, v139, v181
	v_exp_f32_e32 v188, v132
	v_cvt_pk_bf16_f32 v132, v183, v185
	v_cvt_pk_bf16_f32 v133, v187, v189
	v_cvt_pk_bf16_f32 v134, v179, v184
	v_cvt_pk_bf16_f32 v135, v186, v188
	v_mfma_f32_16x16x32_bf16 v[136:139], v[128:131], v[72:75], 0
	s_and_b64 vcc, exec, s[44:45]
	v_mfma_f32_16x16x32_bf16 v[96:99], v[100:103], v[132:135], v[96:99]
	v_mfma_f32_16x16x32_bf16 v[92:95], v[112:115], v[132:135], v[92:95]
	v_mfma_f32_16x16x32_bf16 v[76:79], v[108:111], v[132:135], v[76:79]
	v_mfma_f32_16x16x32_bf16 v[64:67], v[104:107], v[132:135], v[64:67]
	v_mfma_f32_16x16x32_bf16 v[132:135], v[120:123], v[72:75], 0
	v_mfma_f32_16x16x32_bf16 v[132:135], v[124:127], v[68:71], v[132:135]
	v_mfma_f32_16x16x32_bf16 v[136:139], v[116:119], v[68:71], v[136:139]
	s_cbranch_vccnz .LBB0_985
	v_sub_u32_e32 v204, v182, v142
	v_add_u32_e32 v205, 16, v204
	s_and_b64 vcc, exec, s[42:43]
	s_cbranch_vccz .Lam_le_1
	v_cmp_le_i32_e32 vcc, 0, v204
	v_cmp_ge_i32_e64 s[96:97], v204, -1
	v_cmp_ge_i32_e64 s[98:99], v204, -2
	v_cndmask_b32_e32 v132, v241, v132, vcc
	v_cmp_le_i32_e32 vcc, -3, v204
	v_cndmask_b32_e64 v133, v241, v133, s[96:97]
	v_cmp_ge_i32_e64 s[96:97], v205, 0
	v_cndmask_b32_e64 v134, v241, v134, s[98:99]
	v_cmp_ge_i32_e64 s[98:99], v205, -1
	v_cndmask_b32_e32 v135, v241, v135, vcc
	v_cmp_le_i32_e32 vcc, -2, v205
	v_cndmask_b32_e64 v136, v241, v136, s[96:97]
	v_cmp_ge_i32_e64 s[96:97], v205, -3
	v_cndmask_b32_e64 v137, v241, v137, s[98:99]
	v_cndmask_b32_e32 v138, v241, v138, vcc
	v_cndmask_b32_e64 v139, v241, v139, s[96:97]
	s_branch .Lam_done_1

.Lam_done_1:
.LBB0_985:
	s_nop 5
	v_max_f32_e32 v148, v133, v133
	v_max_f32_e32 v149, v132, v132
	v_max_f32_e32 v148, v149, v148
	v_max_f32_e32 v149, v135, v135
	v_max_f32_e32 v152, v134, v134
	v_max_f32_e32 v149, v152, v149
	v_max_f32_e32 v152, v139, v139
	v_max_f32_e32 v153, v138, v138
	v_max_f32_e32 v152, v153, v152
	v_max3_f32 v152, v136, v137, v152
	v_max3_f32 v148, v148, v149, v152
	ds_bpermute_b32 v149, v0, v148
	s_waitcnt lgkmcnt(0)
	v_max_f32_e32 v149, v149, v149
	v_max_f32_e32 v148, v148, v149
	ds_bpermute_b32 v149, v2, v148
	s_waitcnt lgkmcnt(0)
	v_max3_f32 v190, v178, v148, v149
	v_cmp_neq_f32_e32 vcc, v190, v178
	s_cbranch_vccz .LBB0_987
	v_sub_f32_e32 v148, v178, v190
	v_exp_f32_e32 v178, v148
	s_nop 0
	v_mul_f32_e32 v167, v167, v178
	v_pk_mul_f32 v[50:51], v[50:51], v[178:179] op_sel_hi:[1,0]
	v_pk_mul_f32 v[48:49], v[48:49], v[178:179] op_sel_hi:[1,0]
	v_pk_mul_f32 v[46:47], v[46:47], v[178:179] op_sel_hi:[1,0]
	v_pk_mul_f32 v[44:45], v[44:45], v[178:179] op_sel_hi:[1,0]
	v_pk_mul_f32 v[42:43], v[42:43], v[178:179] op_sel_hi:[1,0]
	v_pk_mul_f32 v[40:41], v[40:41], v[178:179] op_sel_hi:[1,0]
	v_pk_mul_f32 v[38:39], v[38:39], v[178:179] op_sel_hi:[1,0]
	v_pk_mul_f32 v[36:37], v[36:37], v[178:179] op_sel_hi:[1,0]
.LBB0_987:
	v_sub_f32_e32 v132, v132, v190
	v_exp_f32_e32 v192, v132
	v_sub_f32_e32 v132, v136, v190
	v_exp_f32_e32 v178, v132
	v_sub_f32_e32 v132, v133, v190
	v_exp_f32_e32 v194, v132
	v_sub_f32_e32 v132, v137, v190
	v_exp_f32_e32 v193, v132
	v_sub_f32_e32 v132, v134, v190
	v_exp_f32_e32 v196, v132
	v_sub_f32_e32 v132, v138, v190
	v_exp_f32_e32 v195, v132
	v_sub_f32_e32 v132, v135, v190
	v_exp_f32_e32 v198, v132
	v_sub_f32_e32 v132, v139, v190
	v_exp_f32_e32 v197, v132
	v_cvt_pk_bf16_f32 v132, v192, v194
	v_cvt_pk_bf16_f32 v133, v196, v198
	v_cvt_pk_bf16_f32 v134, v178, v193
	v_cvt_pk_bf16_f32 v135, v195, v197
	v_mfma_f32_16x16x32_bf16 v[136:139], v[128:131], v[60:63], 0
	s_and_b64 vcc, exec, s[44:45]
	v_mfma_f32_16x16x32_bf16 v[48:51], v[100:103], v[132:135], v[48:51]
	v_mfma_f32_16x16x32_bf16 v[44:47], v[112:115], v[132:135], v[44:47]
	v_mfma_f32_16x16x32_bf16 v[40:43], v[108:111], v[132:135], v[40:43]
	v_mfma_f32_16x16x32_bf16 v[36:39], v[104:107], v[132:135], v[36:39]
	v_mfma_f32_16x16x32_bf16 v[132:135], v[120:123], v[60:63], 0
	v_mfma_f32_16x16x32_bf16 v[132:135], v[124:127], v[56:59], v[132:135]
	v_mfma_f32_16x16x32_bf16 v[136:139], v[116:119], v[56:59], v[136:139]
	s_cbranch_vccnz .LBB0_989
	v_sub_u32_e32 v204, v182, v142
	v_add_u32_e32 v205, 16, v204
	s_and_b64 vcc, exec, s[42:43]
	s_cbranch_vccz .Lam_le_2
	v_cmp_le_i32_e32 vcc, 0, v204
	v_cmp_ge_i32_e64 s[96:97], v204, -1
	v_cmp_ge_i32_e64 s[98:99], v204, -2
	v_cndmask_b32_e32 v132, v241, v132, vcc
	v_cmp_le_i32_e32 vcc, -3, v204
	v_cndmask_b32_e64 v133, v241, v133, s[96:97]
	v_cmp_ge_i32_e64 s[96:97], v205, 0
	v_cndmask_b32_e64 v134, v241, v134, s[98:99]
	v_cmp_ge_i32_e64 s[98:99], v205, -1
	v_cndmask_b32_e32 v135, v241, v135, vcc
	v_cmp_le_i32_e32 vcc, -2, v205
	v_cndmask_b32_e64 v136, v241, v136, s[96:97]
	v_cmp_ge_i32_e64 s[96:97], v205, -3
	v_cndmask_b32_e64 v137, v241, v137, s[98:99]
	v_cndmask_b32_e32 v138, v241, v138, vcc
	v_cndmask_b32_e64 v139, v241, v139, s[96:97]
	s_branch .Lam_done_2

.Lam_done_2:
.LBB0_989:
	s_nop 5
	v_max_f32_e32 v148, v133, v133
	v_max_f32_e32 v149, v132, v132
	v_max_f32_e32 v148, v149, v148
	v_max_f32_e32 v149, v135, v135
	v_max_f32_e32 v152, v134, v134
	v_max_f32_e32 v149, v152, v149
	v_max_f32_e32 v152, v139, v139
	v_max_f32_e32 v153, v138, v138
	v_max_f32_e32 v152, v153, v152
	v_max3_f32 v152, v136, v137, v152
	v_max3_f32 v148, v148, v149, v152
	ds_bpermute_b32 v149, v0, v148
	s_waitcnt lgkmcnt(0)
	v_max_f32_e32 v149, v149, v149
	v_max_f32_e32 v148, v148, v149
	ds_bpermute_b32 v149, v2, v148
	s_waitcnt lgkmcnt(0)
	v_max3_f32 v191, v177, v148, v149
	v_cmp_neq_f32_e32 vcc, v191, v177
	s_cbranch_vccz .LBB0_991
	v_sub_f32_e32 v148, v177, v191
	v_exp_f32_e32 v200, v148
	s_nop 0
	v_mul_f32_e32 v145, v145, v200
	v_pk_mul_f32 v[34:35], v[34:35], v[200:201] op_sel_hi:[1,0]
	v_pk_mul_f32 v[32:33], v[32:33], v[200:201] op_sel_hi:[1,0]
	v_pk_mul_f32 v[30:31], v[30:31], v[200:201] op_sel_hi:[1,0]
	v_pk_mul_f32 v[28:29], v[28:29], v[200:201] op_sel_hi:[1,0]
	v_pk_mul_f32 v[26:27], v[26:27], v[200:201] op_sel_hi:[1,0]
	v_pk_mul_f32 v[24:25], v[24:25], v[200:201] op_sel_hi:[1,0]
	v_pk_mul_f32 v[22:23], v[22:23], v[200:201] op_sel_hi:[1,0]
	v_pk_mul_f32 v[20:21], v[20:21], v[200:201] op_sel_hi:[1,0]
.LBB0_991:
	v_mfma_f32_16x16x32_bf16 v[120:123], v[120:123], v[52:55], 0
	v_sub_f32_e32 v132, v132, v191
	v_sub_f32_e32 v133, v133, v191
	v_sub_f32_e32 v134, v134, v191
	v_sub_f32_e32 v135, v135, v191
	v_exp_f32_e32 v177, v132
	v_sub_f32_e32 v132, v136, v191
	v_exp_f32_e32 v136, v133
	v_sub_f32_e32 v133, v137, v191
	v_exp_f32_e32 v137, v134
	v_sub_f32_e32 v134, v138, v191
	v_exp_f32_e32 v138, v135
	v_sub_f32_e32 v135, v139, v191
	v_exp_f32_e32 v132, v132
	v_exp_f32_e32 v133, v133
	v_exp_f32_e32 v134, v134
	v_exp_f32_e32 v135, v135
	v_mfma_f32_16x16x32_bf16 v[120:123], v[124:127], v[88:91], v[120:123]
	v_cvt_pk_bf16_f32 v200, v177, v136
	v_cvt_pk_bf16_f32 v201, v137, v138
	v_cvt_pk_bf16_f32 v202, v132, v133
	v_mfma_f32_16x16x32_bf16 v[124:127], v[128:131], v[52:55], 0
	v_cvt_pk_bf16_f32 v203, v134, v135
	s_and_b64 vcc, exec, s[44:45]
	s_nop 0
	v_mfma_f32_16x16x32_bf16 v[32:35], v[100:103], v[200:203], v[32:35]
	v_mfma_f32_16x16x32_bf16 v[28:31], v[112:115], v[200:203], v[28:31]
	v_mfma_f32_16x16x32_bf16 v[24:27], v[108:111], v[200:203], v[24:27]
	v_mfma_f32_16x16x32_bf16 v[20:23], v[104:107], v[200:203], v[20:23]
	v_mfma_f32_16x16x32_bf16 v[116:119], v[116:119], v[88:91], v[124:127]
	s_cbranch_vccnz .LBB0_993
	v_sub_u32_e32 v204, v182, v142
	v_add_u32_e32 v205, 16, v204
	s_and_b64 vcc, exec, s[42:43]
	s_cbranch_vccz .Lam_le_3
	v_cmp_le_i32_e32 vcc, 0, v204
	v_cmp_ge_i32_e64 s[96:97], v204, -1
	v_cmp_ge_i32_e64 s[98:99], v204, -2
	v_cndmask_b32_e32 v120, v241, v120, vcc
	v_cmp_le_i32_e32 vcc, -3, v204
	v_cndmask_b32_e64 v121, v241, v121, s[96:97]
	v_cmp_ge_i32_e64 s[96:97], v205, 0
	v_cndmask_b32_e64 v122, v241, v122, s[98:99]
	v_cmp_ge_i32_e64 s[98:99], v205, -1
	v_cndmask_b32_e32 v123, v241, v123, vcc
	v_cmp_le_i32_e32 vcc, -2, v205
	v_cndmask_b32_e64 v116, v241, v116, s[96:97]
	v_cmp_ge_i32_e64 s[96:97], v205, -3
	v_cndmask_b32_e64 v117, v241, v117, s[98:99]
	v_cndmask_b32_e32 v118, v241, v118, vcc
	v_cndmask_b32_e64 v119, v241, v119, s[96:97]
	s_branch .Lam_done_3
.Lam_le_3:
	v_cmp_ge_i32_e32 vcc, 0, v204
	v_cmp_le_i32_e64 s[96:97], v204, -1
	v_cmp_le_i32_e64 s[98:99], v204, -2
	v_cndmask_b32_e32 v120, v241, v120, vcc
	v_cmp_ge_i32_e32 vcc, -3, v204
	v_cndmask_b32_e64 v121, v241, v121, s[96:97]
	v_cmp_le_i32_e64 s[96:97], v205, 0
	v_cndmask_b32_e64 v122, v241, v122, s[98:99]
	v_cmp_le_i32_e64 s[98:99], v205, -1
	v_cndmask_b32_e32 v123, v241, v123, vcc
	v_cmp_ge_i32_e32 vcc, -2, v205
	v_cndmask_b32_e64 v116, v241, v116, s[96:97]
	v_cmp_le_i32_e64 s[96:97], v205, -3
	v_cndmask_b32_e64 v117, v241, v117, s[98:99]
	v_cndmask_b32_e32 v118, v241, v118, vcc
	v_cndmask_b32_e64 v119, v241, v119, s[96:97]
.Lam_done_3:
.LBB0_993:
	s_nop 1
	v_max_f32_e32 v124, v121, v121
	v_max_f32_e32 v125, v120, v120
	v_max_f32_e32 v124, v125, v124
	v_max_f32_e32 v125, v123, v123
	v_max_f32_e32 v126, v122, v122
	v_max_f32_e32 v125, v126, v125
	v_max_f32_e32 v126, v119, v119
	v_max_f32_e32 v127, v118, v118
	v_max_f32_e32 v126, v127, v126
	v_max3_f32 v126, v116, v117, v126
	v_max3_f32 v124, v124, v125, v126
	ds_bpermute_b32 v125, v0, v124
	s_waitcnt lgkmcnt(0)
	v_max_f32_e32 v125, v125, v125
	v_max_f32_e32 v124, v124, v125
	ds_bpermute_b32 v125, v2, v124
	s_waitcnt lgkmcnt(0)
	v_max3_f32 v124, v176, v124, v125
	v_cmp_neq_f32_e32 vcc, v124, v176
	s_cbranch_vccz .LBB0_995
	v_sub_f32_e32 v125, v176, v124
	v_exp_f32_e32 v126, v125
	s_nop 0
	v_mul_f32_e32 v143, v143, v126
	v_pk_mul_f32 v[18:19], v[18:19], v[126:127] op_sel_hi:[1,0]
	v_pk_mul_f32 v[16:17], v[16:17], v[126:127] op_sel_hi:[1,0]
	v_pk_mul_f32 v[14:15], v[14:15], v[126:127] op_sel_hi:[1,0]
	v_pk_mul_f32 v[12:13], v[12:13], v[126:127] op_sel_hi:[1,0]
	v_pk_mul_f32 v[10:11], v[10:11], v[126:127] op_sel_hi:[1,0]
	v_pk_mul_f32 v[8:9], v[8:9], v[126:127] op_sel_hi:[1,0]
	v_pk_mul_f32 v[6:7], v[6:7], v[126:127] op_sel_hi:[1,0]
	v_pk_mul_f32 v[4:5], v[4:5], v[126:127] op_sel_hi:[1,0]
